# stack13: stack12 + kvc_fix_rows W2T row loads all issued up front, dot loop unrolled over 8 register blocks
# baseline (speedup 1.0000x reference)
.LBB0_1210:
	s_ashr_i32 s0, s10, 1
	s_ashr_i32 s1, s0, 31
	s_lshl_b64 s[0:1], s[0:1], 9
	s_add_u32 s4, s0, s8
	s_addc_u32 s5, s1, 0
	s_lshl_b64 s[0:1], s[4:5], 9
	v_lshl_add_u64 v[12:13], v[2:3], 0, s[0:1]
	global_load_ushort v11, v[12:13], off offset:768
	global_load_ushort v14, v[12:13], off
	global_load_ushort v15, v[12:13], off offset:896
	s_nop 0
	global_load_ushort v12, v[12:13], off offset:128
	v_add_co_u32_e32 v50, vcc, 0x2a80000, v6
	s_nop 1
	v_addc_co_u32_e32 v51, vcc, 0, v7, vcc
	global_load_dwordx4 v[52:55], v[50:51], off offset:128
	global_load_dwordx4 v[56:59], v[50:51], off
	global_load_dwordx4 v[98:101], v[50:51], off offset:144
	global_load_dwordx4 v[102:105], v[50:51], off offset:16
	global_load_dwordx4 v[106:109], v[50:51], off offset:160
	global_load_dwordx4 v[110:113], v[50:51], off offset:32
	global_load_dwordx4 v[114:117], v[50:51], off offset:176
	global_load_dwordx4 v[118:121], v[50:51], off offset:48
	global_load_dwordx4 v[146:149], v[50:51], off offset:192
	global_load_dwordx4 v[150:153], v[50:51], off offset:64
	global_load_dwordx4 v[204:207], v[50:51], off offset:208
	global_load_dwordx4 v[208:211], v[50:51], off offset:80
	global_load_dwordx4 v[216:219], v[50:51], off offset:224
	global_load_dwordx4 v[220:223], v[50:51], off offset:96
	global_load_dwordx4 v[224:227], v[50:51], off offset:240
	global_load_dwordx4 v[228:231], v[50:51], off offset:112
	s_mov_b64 s[6:7], 0
	s_waitcnt vmcnt(3)
	v_lshlrev_b32_e32 v11, 16, v11
	s_waitcnt vmcnt(2)
	v_lshlrev_b32_e32 v13, 16, v14
	s_waitcnt vmcnt(1)
	v_lshlrev_b32_e32 v14, 16, v15
	s_waitcnt vmcnt(0)
	v_lshlrev_b32_e32 v12, 16, v12
	v_add_f32_e32 v11, v11, v13
	v_add_f32_e32 v12, v14, v12
	v_add_f32_e32 v13, v1, v11
	v_add_f32_e32 v12, v8, v12
	v_mul_f32_e32 v11, 0x3d372713, v13
	v_mul_f32_e32 v14, 0x3d372713, v12
	v_mul_f32_e32 v11, v13, v11
	v_mul_f32_e32 v14, v12, v14
	v_fma_f32 v11, v13, v11, v13
	v_fma_f32 v14, v12, v14, v12
	v_mul_f32_e32 v11, 0xbfcc422a, v11
	v_mul_f32_e32 v14, 0xbfcc422a, v14
	v_mul_f32_e32 v11, 0x3fb8aa3b, v11
	v_mul_f32_e32 v14, 0x3fb8aa3b, v14
	v_exp_f32_e32 v15, v11
	v_exp_f32_e32 v14, v14
	v_mov_b32_e32 v11, v10
	v_add_f32_e32 v15, 1.0, v15
	v_add_f32_e32 v14, 1.0, v14
	v_div_scale_f32 v16, s[0:1], v15, v15, v13
	v_div_scale_f32 v18, s[0:1], v14, v14, v12
	v_rcp_f32_e32 v19, v16
	v_rcp_f32_e32 v20, v18
	v_div_scale_f32 v17, vcc, v13, v15, v13
	v_fma_f32 v22, -v16, v19, 1.0
	v_fma_f32 v23, -v18, v20, 1.0
	v_fmac_f32_e32 v19, v22, v19
	v_div_scale_f32 v21, s[0:1], v12, v14, v12
	v_fmac_f32_e32 v20, v23, v20
	v_mul_f32_e32 v22, v17, v19
	v_mul_f32_e32 v23, v21, v20
	v_fma_f32 v24, -v16, v22, v17
	v_fma_f32 v25, -v18, v23, v21
	v_fmac_f32_e32 v22, v24, v19
	v_fmac_f32_e32 v23, v25, v20
	v_fma_f32 v16, -v16, v22, v17
	v_fma_f32 v17, -v18, v23, v21
	v_div_fmas_f32 v16, v16, v19, v22
	s_mov_b64 vcc, s[0:1]
	v_div_fixup_f32 v13, v16, v15, v13
	v_div_fmas_f32 v15, v17, v20, v23
	v_div_fixup_f32 v14, v15, v14, v12
	v_cvt_pk_bf16_f32 v12, v13, 0
	v_cvt_pk_bf16_f32 v13, v14, 0
	v_lshlrev_b32_e32 v12, 16, v12
	v_lshlrev_b32_e32 v13, 16, v13
	v_mov_b32_e32 v14, v9
.LBB0_1211:
	s_waitcnt vmcnt(0)
	v_subrev_u32_e32 v15, 28, v11
	s_nop 0
	s_nop 0
	v_subrev_u32_e32 v29, 24, v11
	ds_bpermute_b32 v26, v15, v12
	ds_bpermute_b32 v27, v15, v13
	v_subrev_u32_e32 v31, 20, v11
	ds_bpermute_b32 v28, v29, v12
	ds_bpermute_b32 v29, v29, v13
	v_add_u32_e32 v33, -16, v11
	ds_bpermute_b32 v30, v31, v12
	ds_bpermute_b32 v31, v31, v13
	v_add_u32_e32 v35, -12, v11
	ds_bpermute_b32 v32, v33, v12
	ds_bpermute_b32 v33, v33, v13
	v_add_u32_e32 v37, -8, v11
	ds_bpermute_b32 v34, v35, v12
	ds_bpermute_b32 v35, v35, v13
	v_add_u32_e32 v39, -4, v11
	ds_bpermute_b32 v36, v37, v12
	ds_bpermute_b32 v37, v37, v13
	ds_bpermute_b32 v38, v39, v12
	ds_bpermute_b32 v39, v39, v13
	ds_bpermute_b32 v24, v11, v12
	ds_bpermute_b32 v25, v11, v13
	v_add_u32_e32 v11, 32, v11
	v_lshlrev_b32_e32 v41, 16, v52
	v_lshlrev_b32_e32 v40, 16, v56
	v_and_b32_e32 v43, 0xffff0000, v52
	v_and_b32_e32 v42, 0xffff0000, v56
	v_lshlrev_b32_e32 v44, 16, v57
	v_and_b32_e32 v52, 0xffff0000, v57
	v_lshlrev_b32_e32 v57, 16, v54
	v_lshlrev_b32_e32 v56, 16, v58
	v_and_b32_e32 v47, 0xffff0000, v54
	v_and_b32_e32 v46, 0xffff0000, v58
	v_lshlrev_b32_e32 v48, 16, v59
	v_and_b32_e32 v54, 0xffff0000, v59
	s_waitcnt lgkmcnt(14)
	v_pk_mul_f32 v[58:59], v[26:27], v[40:41]
	v_lshlrev_b32_e32 v45, 16, v53
	s_waitcnt lgkmcnt(12)
	v_pk_mul_f32 v[26:27], v[28:29], v[42:43]
	v_add_f32_e32 v15, v58, v59
	v_and_b32_e32 v53, 0xffff0000, v53
	s_waitcnt lgkmcnt(10)
	v_pk_mul_f32 v[28:29], v[30:31], v[44:45]
	v_add_f32_e32 v58, v26, v27
	v_add_f32_e32 v14, v14, v15
	s_waitcnt lgkmcnt(8)
	v_pk_mul_f32 v[52:53], v[32:33], v[52:53]
	v_add_f32_e32 v59, v28, v29
	v_add_f32_e32 v14, v14, v58
	s_waitcnt lgkmcnt(6)
	v_pk_mul_f32 v[56:57], v[34:35], v[56:57]
	v_add_f32_e32 v52, v52, v53
	v_add_f32_e32 v14, v14, v59
	v_lshlrev_b32_e32 v49, 16, v55
	s_waitcnt lgkmcnt(4)
	v_pk_mul_f32 v[30:31], v[36:37], v[46:47]
	v_add_f32_e32 v53, v56, v57
	v_add_f32_e32 v14, v14, v52
	v_and_b32_e32 v55, 0xffff0000, v55
	s_waitcnt lgkmcnt(2)
	v_pk_mul_f32 v[32:33], v[38:39], v[48:49]
	v_add_f32_e32 v56, v30, v31
	v_add_f32_e32 v14, v14, v53
	s_waitcnt lgkmcnt(0)
	v_pk_mul_f32 v[54:55], v[24:25], v[54:55]
	v_add_f32_e32 v57, v32, v33
	v_add_f32_e32 v14, v14, v56
	v_add_f32_e32 v54, v54, v55
	v_add_f32_e32 v14, v14, v57
	v_add_f32_e32 v14, v14, v54
	v_subrev_u32_e32 v15, 28, v11
	s_nop 0
	s_nop 0
	v_subrev_u32_e32 v29, 24, v11
	ds_bpermute_b32 v26, v15, v12
	ds_bpermute_b32 v27, v15, v13
	v_subrev_u32_e32 v31, 20, v11
	ds_bpermute_b32 v28, v29, v12
	ds_bpermute_b32 v29, v29, v13
	v_add_u32_e32 v33, -16, v11
	ds_bpermute_b32 v30, v31, v12
	ds_bpermute_b32 v31, v31, v13
	v_add_u32_e32 v35, -12, v11
	ds_bpermute_b32 v32, v33, v12
	ds_bpermute_b32 v33, v33, v13
	v_add_u32_e32 v37, -8, v11
	ds_bpermute_b32 v34, v35, v12
	ds_bpermute_b32 v35, v35, v13
	v_add_u32_e32 v39, -4, v11
	ds_bpermute_b32 v36, v37, v12
	ds_bpermute_b32 v37, v37, v13
	ds_bpermute_b32 v38, v39, v12
	ds_bpermute_b32 v39, v39, v13
	ds_bpermute_b32 v24, v11, v12
	ds_bpermute_b32 v25, v11, v13
	v_add_u32_e32 v11, 32, v11
	v_lshlrev_b32_e32 v41, 16, v98
	v_lshlrev_b32_e32 v40, 16, v102
	v_and_b32_e32 v43, 0xffff0000, v98
	v_and_b32_e32 v42, 0xffff0000, v102
	v_lshlrev_b32_e32 v44, 16, v103
	v_and_b32_e32 v98, 0xffff0000, v103
	v_lshlrev_b32_e32 v103, 16, v100
	v_lshlrev_b32_e32 v102, 16, v104
	v_and_b32_e32 v47, 0xffff0000, v100
	v_and_b32_e32 v46, 0xffff0000, v104
	v_lshlrev_b32_e32 v48, 16, v105
	v_and_b32_e32 v100, 0xffff0000, v105
	s_waitcnt lgkmcnt(14)
	v_pk_mul_f32 v[104:105], v[26:27], v[40:41]
	v_lshlrev_b32_e32 v45, 16, v99
	s_waitcnt lgkmcnt(12)
	v_pk_mul_f32 v[26:27], v[28:29], v[42:43]
	v_add_f32_e32 v15, v104, v105
	v_and_b32_e32 v99, 0xffff0000, v99
	s_waitcnt lgkmcnt(10)
	v_pk_mul_f32 v[28:29], v[30:31], v[44:45]
	v_add_f32_e32 v104, v26, v27
	v_add_f32_e32 v14, v14, v15
	s_waitcnt lgkmcnt(8)
	v_pk_mul_f32 v[98:99], v[32:33], v[98:99]
	v_add_f32_e32 v105, v28, v29
	v_add_f32_e32 v14, v14, v104
	s_waitcnt lgkmcnt(6)
	v_pk_mul_f32 v[102:103], v[34:35], v[102:103]
	v_add_f32_e32 v98, v98, v99
	v_add_f32_e32 v14, v14, v105
	v_lshlrev_b32_e32 v49, 16, v101
	s_waitcnt lgkmcnt(4)
	v_pk_mul_f32 v[30:31], v[36:37], v[46:47]
	v_add_f32_e32 v99, v102, v103
	v_add_f32_e32 v14, v14, v98
	v_and_b32_e32 v101, 0xffff0000, v101
	s_waitcnt lgkmcnt(2)
	v_pk_mul_f32 v[32:33], v[38:39], v[48:49]
	v_add_f32_e32 v102, v30, v31
	v_add_f32_e32 v14, v14, v99
	s_waitcnt lgkmcnt(0)
	v_pk_mul_f32 v[100:101], v[24:25], v[100:101]
	v_add_f32_e32 v103, v32, v33
	v_add_f32_e32 v14, v14, v102
	v_add_f32_e32 v100, v100, v101
	v_add_f32_e32 v14, v14, v103
	v_add_f32_e32 v14, v14, v100
	v_subrev_u32_e32 v15, 28, v11
	s_nop 0
	s_nop 0
	v_subrev_u32_e32 v29, 24, v11
	ds_bpermute_b32 v26, v15, v12
	ds_bpermute_b32 v27, v15, v13
	v_subrev_u32_e32 v31, 20, v11
	ds_bpermute_b32 v28, v29, v12
	ds_bpermute_b32 v29, v29, v13
	v_add_u32_e32 v33, -16, v11
	ds_bpermute_b32 v30, v31, v12
	ds_bpermute_b32 v31, v31, v13
	v_add_u32_e32 v35, -12, v11
	ds_bpermute_b32 v32, v33, v12
	ds_bpermute_b32 v33, v33, v13
	v_add_u32_e32 v37, -8, v11
	ds_bpermute_b32 v34, v35, v12
	ds_bpermute_b32 v35, v35, v13
	v_add_u32_e32 v39, -4, v11
	ds_bpermute_b32 v36, v37, v12
	ds_bpermute_b32 v37, v37, v13
	ds_bpermute_b32 v38, v39, v12
	ds_bpermute_b32 v39, v39, v13
	ds_bpermute_b32 v24, v11, v12
	ds_bpermute_b32 v25, v11, v13
	v_add_u32_e32 v11, 32, v11
	v_lshlrev_b32_e32 v41, 16, v106
	v_lshlrev_b32_e32 v40, 16, v110
	v_and_b32_e32 v43, 0xffff0000, v106
	v_and_b32_e32 v42, 0xffff0000, v110
	v_lshlrev_b32_e32 v44, 16, v111
	v_and_b32_e32 v106, 0xffff0000, v111
	v_lshlrev_b32_e32 v111, 16, v108
	v_lshlrev_b32_e32 v110, 16, v112
	v_and_b32_e32 v47, 0xffff0000, v108
	v_and_b32_e32 v46, 0xffff0000, v112
	v_lshlrev_b32_e32 v48, 16, v113
	v_and_b32_e32 v108, 0xffff0000, v113
	s_waitcnt lgkmcnt(14)
	v_pk_mul_f32 v[112:113], v[26:27], v[40:41]
	v_lshlrev_b32_e32 v45, 16, v107
	s_waitcnt lgkmcnt(12)
	v_pk_mul_f32 v[26:27], v[28:29], v[42:43]
	v_add_f32_e32 v15, v112, v113
	v_and_b32_e32 v107, 0xffff0000, v107
	s_waitcnt lgkmcnt(10)
	v_pk_mul_f32 v[28:29], v[30:31], v[44:45]
	v_add_f32_e32 v112, v26, v27
	v_add_f32_e32 v14, v14, v15
	s_waitcnt lgkmcnt(8)
	v_pk_mul_f32 v[106:107], v[32:33], v[106:107]
	v_add_f32_e32 v113, v28, v29
	v_add_f32_e32 v14, v14, v112
	s_waitcnt lgkmcnt(6)
	v_pk_mul_f32 v[110:111], v[34:35], v[110:111]
	v_add_f32_e32 v106, v106, v107
	v_add_f32_e32 v14, v14, v113
	v_lshlrev_b32_e32 v49, 16, v109
	s_waitcnt lgkmcnt(4)
	v_pk_mul_f32 v[30:31], v[36:37], v[46:47]
	v_add_f32_e32 v107, v110, v111
	v_add_f32_e32 v14, v14, v106
	v_and_b32_e32 v109, 0xffff0000, v109
	s_waitcnt lgkmcnt(2)
	v_pk_mul_f32 v[32:33], v[38:39], v[48:49]
	v_add_f32_e32 v110, v30, v31
	v_add_f32_e32 v14, v14, v107
	s_waitcnt lgkmcnt(0)
	v_pk_mul_f32 v[108:109], v[24:25], v[108:109]
	v_add_f32_e32 v111, v32, v33
	v_add_f32_e32 v14, v14, v110
	v_add_f32_e32 v108, v108, v109
	v_add_f32_e32 v14, v14, v111
	v_add_f32_e32 v14, v14, v108
	v_subrev_u32_e32 v15, 28, v11
	s_nop 0
	s_nop 0
	v_subrev_u32_e32 v29, 24, v11
	ds_bpermute_b32 v26, v15, v12
	ds_bpermute_b32 v27, v15, v13
	v_subrev_u32_e32 v31, 20, v11
	ds_bpermute_b32 v28, v29, v12
	ds_bpermute_b32 v29, v29, v13
	v_add_u32_e32 v33, -16, v11
	ds_bpermute_b32 v30, v31, v12
	ds_bpermute_b32 v31, v31, v13
	v_add_u32_e32 v35, -12, v11
	ds_bpermute_b32 v32, v33, v12
	ds_bpermute_b32 v33, v33, v13
	v_add_u32_e32 v37, -8, v11
	ds_bpermute_b32 v34, v35, v12
	ds_bpermute_b32 v35, v35, v13
	v_add_u32_e32 v39, -4, v11
	ds_bpermute_b32 v36, v37, v12
	ds_bpermute_b32 v37, v37, v13
	ds_bpermute_b32 v38, v39, v12
	ds_bpermute_b32 v39, v39, v13
	ds_bpermute_b32 v24, v11, v12
	ds_bpermute_b32 v25, v11, v13
	v_add_u32_e32 v11, 32, v11
	v_lshlrev_b32_e32 v41, 16, v114
	v_lshlrev_b32_e32 v40, 16, v118
	v_and_b32_e32 v43, 0xffff0000, v114
	v_and_b32_e32 v42, 0xffff0000, v118
	v_lshlrev_b32_e32 v44, 16, v119
	v_and_b32_e32 v114, 0xffff0000, v119
	v_lshlrev_b32_e32 v119, 16, v116
	v_lshlrev_b32_e32 v118, 16, v120
	v_and_b32_e32 v47, 0xffff0000, v116
	v_and_b32_e32 v46, 0xffff0000, v120
	v_lshlrev_b32_e32 v48, 16, v121
	v_and_b32_e32 v116, 0xffff0000, v121
	s_waitcnt lgkmcnt(14)
	v_pk_mul_f32 v[120:121], v[26:27], v[40:41]
	v_lshlrev_b32_e32 v45, 16, v115
	s_waitcnt lgkmcnt(12)
	v_pk_mul_f32 v[26:27], v[28:29], v[42:43]
	v_add_f32_e32 v15, v120, v121
	v_and_b32_e32 v115, 0xffff0000, v115
	s_waitcnt lgkmcnt(10)
	v_pk_mul_f32 v[28:29], v[30:31], v[44:45]
	v_add_f32_e32 v120, v26, v27
	v_add_f32_e32 v14, v14, v15
	s_waitcnt lgkmcnt(8)
	v_pk_mul_f32 v[114:115], v[32:33], v[114:115]
	v_add_f32_e32 v121, v28, v29
	v_add_f32_e32 v14, v14, v120
	s_waitcnt lgkmcnt(6)
	v_pk_mul_f32 v[118:119], v[34:35], v[118:119]
	v_add_f32_e32 v114, v114, v115
	v_add_f32_e32 v14, v14, v121
	v_lshlrev_b32_e32 v49, 16, v117
	s_waitcnt lgkmcnt(4)
	v_pk_mul_f32 v[30:31], v[36:37], v[46:47]
	v_add_f32_e32 v115, v118, v119
	v_add_f32_e32 v14, v14, v114
	v_and_b32_e32 v117, 0xffff0000, v117
	s_waitcnt lgkmcnt(2)
	v_pk_mul_f32 v[32:33], v[38:39], v[48:49]
	v_add_f32_e32 v118, v30, v31
	v_add_f32_e32 v14, v14, v115
	s_waitcnt lgkmcnt(0)
	v_pk_mul_f32 v[116:117], v[24:25], v[116:117]
	v_add_f32_e32 v119, v32, v33
	v_add_f32_e32 v14, v14, v118
	v_add_f32_e32 v116, v116, v117
	v_add_f32_e32 v14, v14, v119
	v_add_f32_e32 v14, v14, v116
	v_subrev_u32_e32 v15, 28, v11
	s_nop 0
	s_nop 0
	v_subrev_u32_e32 v29, 24, v11
	ds_bpermute_b32 v26, v15, v12
	ds_bpermute_b32 v27, v15, v13
	v_subrev_u32_e32 v31, 20, v11
	ds_bpermute_b32 v28, v29, v12
	ds_bpermute_b32 v29, v29, v13
	v_add_u32_e32 v33, -16, v11
	ds_bpermute_b32 v30, v31, v12
	ds_bpermute_b32 v31, v31, v13
	v_add_u32_e32 v35, -12, v11
	ds_bpermute_b32 v32, v33, v12
	ds_bpermute_b32 v33, v33, v13
	v_add_u32_e32 v37, -8, v11
	ds_bpermute_b32 v34, v35, v12
	ds_bpermute_b32 v35, v35, v13
	v_add_u32_e32 v39, -4, v11
	ds_bpermute_b32 v36, v37, v12
	ds_bpermute_b32 v37, v37, v13
	ds_bpermute_b32 v38, v39, v12
	ds_bpermute_b32 v39, v39, v13
	ds_bpermute_b32 v24, v11, v12
	ds_bpermute_b32 v25, v11, v13
	v_add_u32_e32 v11, 32, v11
	v_lshlrev_b32_e32 v41, 16, v146
	v_lshlrev_b32_e32 v40, 16, v150
	v_and_b32_e32 v43, 0xffff0000, v146
	v_and_b32_e32 v42, 0xffff0000, v150
	v_lshlrev_b32_e32 v44, 16, v151
	v_and_b32_e32 v146, 0xffff0000, v151
	v_lshlrev_b32_e32 v151, 16, v148
	v_lshlrev_b32_e32 v150, 16, v152
	v_and_b32_e32 v47, 0xffff0000, v148
	v_and_b32_e32 v46, 0xffff0000, v152
	v_lshlrev_b32_e32 v48, 16, v153
	v_and_b32_e32 v148, 0xffff0000, v153
	s_waitcnt lgkmcnt(14)
	v_pk_mul_f32 v[152:153], v[26:27], v[40:41]
	v_lshlrev_b32_e32 v45, 16, v147
	s_waitcnt lgkmcnt(12)
	v_pk_mul_f32 v[26:27], v[28:29], v[42:43]
	v_add_f32_e32 v15, v152, v153
	v_and_b32_e32 v147, 0xffff0000, v147
	s_waitcnt lgkmcnt(10)
	v_pk_mul_f32 v[28:29], v[30:31], v[44:45]
	v_add_f32_e32 v152, v26, v27
	v_add_f32_e32 v14, v14, v15
	s_waitcnt lgkmcnt(8)
	v_pk_mul_f32 v[146:147], v[32:33], v[146:147]
	v_add_f32_e32 v153, v28, v29
	v_add_f32_e32 v14, v14, v152
	s_waitcnt lgkmcnt(6)
	v_pk_mul_f32 v[150:151], v[34:35], v[150:151]
	v_add_f32_e32 v146, v146, v147
	v_add_f32_e32 v14, v14, v153
	v_lshlrev_b32_e32 v49, 16, v149
	s_waitcnt lgkmcnt(4)
	v_pk_mul_f32 v[30:31], v[36:37], v[46:47]
	v_add_f32_e32 v147, v150, v151
	v_add_f32_e32 v14, v14, v146
	v_and_b32_e32 v149, 0xffff0000, v149
	s_waitcnt lgkmcnt(2)
	v_pk_mul_f32 v[32:33], v[38:39], v[48:49]
	v_add_f32_e32 v150, v30, v31
	v_add_f32_e32 v14, v14, v147
	s_waitcnt lgkmcnt(0)
	v_pk_mul_f32 v[148:149], v[24:25], v[148:149]
	v_add_f32_e32 v151, v32, v33
	v_add_f32_e32 v14, v14, v150
	v_add_f32_e32 v148, v148, v149
	v_add_f32_e32 v14, v14, v151
	v_add_f32_e32 v14, v14, v148
	v_subrev_u32_e32 v15, 28, v11
	s_nop 0
	s_nop 0
	v_subrev_u32_e32 v29, 24, v11
	ds_bpermute_b32 v26, v15, v12
	ds_bpermute_b32 v27, v15, v13
	v_subrev_u32_e32 v31, 20, v11
	ds_bpermute_b32 v28, v29, v12
	ds_bpermute_b32 v29, v29, v13
	v_add_u32_e32 v33, -16, v11
	ds_bpermute_b32 v30, v31, v12
	ds_bpermute_b32 v31, v31, v13
	v_add_u32_e32 v35, -12, v11
	ds_bpermute_b32 v32, v33, v12
	ds_bpermute_b32 v33, v33, v13
	v_add_u32_e32 v37, -8, v11
	ds_bpermute_b32 v34, v35, v12
	ds_bpermute_b32 v35, v35, v13
	v_add_u32_e32 v39, -4, v11
	ds_bpermute_b32 v36, v37, v12
	ds_bpermute_b32 v37, v37, v13
	ds_bpermute_b32 v38, v39, v12
	ds_bpermute_b32 v39, v39, v13
	ds_bpermute_b32 v24, v11, v12
	ds_bpermute_b32 v25, v11, v13
	v_add_u32_e32 v11, 32, v11
	v_lshlrev_b32_e32 v41, 16, v204
	v_lshlrev_b32_e32 v40, 16, v208
	v_and_b32_e32 v43, 0xffff0000, v204
	v_and_b32_e32 v42, 0xffff0000, v208
	v_lshlrev_b32_e32 v44, 16, v209
	v_and_b32_e32 v204, 0xffff0000, v209
	v_lshlrev_b32_e32 v209, 16, v206
	v_lshlrev_b32_e32 v208, 16, v210
	v_and_b32_e32 v47, 0xffff0000, v206
	v_and_b32_e32 v46, 0xffff0000, v210
	v_lshlrev_b32_e32 v48, 16, v211
	v_and_b32_e32 v206, 0xffff0000, v211
	s_waitcnt lgkmcnt(14)
	v_pk_mul_f32 v[210:211], v[26:27], v[40:41]
	v_lshlrev_b32_e32 v45, 16, v205
	s_waitcnt lgkmcnt(12)
	v_pk_mul_f32 v[26:27], v[28:29], v[42:43]
	v_add_f32_e32 v15, v210, v211
	v_and_b32_e32 v205, 0xffff0000, v205
	s_waitcnt lgkmcnt(10)
	v_pk_mul_f32 v[28:29], v[30:31], v[44:45]
	v_add_f32_e32 v210, v26, v27
	v_add_f32_e32 v14, v14, v15
	s_waitcnt lgkmcnt(8)
	v_pk_mul_f32 v[204:205], v[32:33], v[204:205]
	v_add_f32_e32 v211, v28, v29
	v_add_f32_e32 v14, v14, v210
	s_waitcnt lgkmcnt(6)
	v_pk_mul_f32 v[208:209], v[34:35], v[208:209]
	v_add_f32_e32 v204, v204, v205
	v_add_f32_e32 v14, v14, v211
	v_lshlrev_b32_e32 v49, 16, v207
	s_waitcnt lgkmcnt(4)
	v_pk_mul_f32 v[30:31], v[36:37], v[46:47]
	v_add_f32_e32 v205, v208, v209
	v_add_f32_e32 v14, v14, v204
	v_and_b32_e32 v207, 0xffff0000, v207
	s_waitcnt lgkmcnt(2)
	v_pk_mul_f32 v[32:33], v[38:39], v[48:49]
	v_add_f32_e32 v208, v30, v31
	v_add_f32_e32 v14, v14, v205
	s_waitcnt lgkmcnt(0)
	v_pk_mul_f32 v[206:207], v[24:25], v[206:207]
	v_add_f32_e32 v209, v32, v33
	v_add_f32_e32 v14, v14, v208
	v_add_f32_e32 v206, v206, v207
	v_add_f32_e32 v14, v14, v209
	v_add_f32_e32 v14, v14, v206
	v_subrev_u32_e32 v15, 28, v11
	s_nop 0
	s_nop 0
	v_subrev_u32_e32 v29, 24, v11
	ds_bpermute_b32 v26, v15, v12
	ds_bpermute_b32 v27, v15, v13
	v_subrev_u32_e32 v31, 20, v11
	ds_bpermute_b32 v28, v29, v12
	ds_bpermute_b32 v29, v29, v13
	v_add_u32_e32 v33, -16, v11
	ds_bpermute_b32 v30, v31, v12
	ds_bpermute_b32 v31, v31, v13
	v_add_u32_e32 v35, -12, v11
	ds_bpermute_b32 v32, v33, v12
	ds_bpermute_b32 v33, v33, v13
	v_add_u32_e32 v37, -8, v11
	ds_bpermute_b32 v34, v35, v12
	ds_bpermute_b32 v35, v35, v13
	v_add_u32_e32 v39, -4, v11
	ds_bpermute_b32 v36, v37, v12
	ds_bpermute_b32 v37, v37, v13
	ds_bpermute_b32 v38, v39, v12
	ds_bpermute_b32 v39, v39, v13
	ds_bpermute_b32 v24, v11, v12
	ds_bpermute_b32 v25, v11, v13
	v_add_u32_e32 v11, 32, v11
	v_lshlrev_b32_e32 v41, 16, v216
	v_lshlrev_b32_e32 v40, 16, v220
	v_and_b32_e32 v43, 0xffff0000, v216
	v_and_b32_e32 v42, 0xffff0000, v220
	v_lshlrev_b32_e32 v44, 16, v221
	v_and_b32_e32 v216, 0xffff0000, v221
	v_lshlrev_b32_e32 v221, 16, v218
	v_lshlrev_b32_e32 v220, 16, v222
	v_and_b32_e32 v47, 0xffff0000, v218
	v_and_b32_e32 v46, 0xffff0000, v222
	v_lshlrev_b32_e32 v48, 16, v223
	v_and_b32_e32 v218, 0xffff0000, v223
	s_waitcnt lgkmcnt(14)
	v_pk_mul_f32 v[222:223], v[26:27], v[40:41]
	v_lshlrev_b32_e32 v45, 16, v217
	s_waitcnt lgkmcnt(12)
	v_pk_mul_f32 v[26:27], v[28:29], v[42:43]
	v_add_f32_e32 v15, v222, v223
	v_and_b32_e32 v217, 0xffff0000, v217
	s_waitcnt lgkmcnt(10)
	v_pk_mul_f32 v[28:29], v[30:31], v[44:45]
	v_add_f32_e32 v222, v26, v27
	v_add_f32_e32 v14, v14, v15
	s_waitcnt lgkmcnt(8)
	v_pk_mul_f32 v[216:217], v[32:33], v[216:217]
	v_add_f32_e32 v223, v28, v29
	v_add_f32_e32 v14, v14, v222
	s_waitcnt lgkmcnt(6)
	v_pk_mul_f32 v[220:221], v[34:35], v[220:221]
	v_add_f32_e32 v216, v216, v217
	v_add_f32_e32 v14, v14, v223
	v_lshlrev_b32_e32 v49, 16, v219
	s_waitcnt lgkmcnt(4)
	v_pk_mul_f32 v[30:31], v[36:37], v[46:47]
	v_add_f32_e32 v217, v220, v221
	v_add_f32_e32 v14, v14, v216
	v_and_b32_e32 v219, 0xffff0000, v219
	s_waitcnt lgkmcnt(2)
	v_pk_mul_f32 v[32:33], v[38:39], v[48:49]
	v_add_f32_e32 v220, v30, v31
	v_add_f32_e32 v14, v14, v217
	s_waitcnt lgkmcnt(0)
	v_pk_mul_f32 v[218:219], v[24:25], v[218:219]
	v_add_f32_e32 v221, v32, v33
	v_add_f32_e32 v14, v14, v220
	v_add_f32_e32 v218, v218, v219
	v_add_f32_e32 v14, v14, v221
	v_add_f32_e32 v14, v14, v218
	v_subrev_u32_e32 v15, 28, v11
	s_nop 0
	s_nop 0
	v_subrev_u32_e32 v29, 24, v11
	ds_bpermute_b32 v26, v15, v12
	ds_bpermute_b32 v27, v15, v13
	v_subrev_u32_e32 v31, 20, v11
	ds_bpermute_b32 v28, v29, v12
	ds_bpermute_b32 v29, v29, v13
	v_add_u32_e32 v33, -16, v11
	ds_bpermute_b32 v30, v31, v12
	ds_bpermute_b32 v31, v31, v13
	v_add_u32_e32 v35, -12, v11
	ds_bpermute_b32 v32, v33, v12
	ds_bpermute_b32 v33, v33, v13
	v_add_u32_e32 v37, -8, v11
	ds_bpermute_b32 v34, v35, v12
	ds_bpermute_b32 v35, v35, v13
	v_add_u32_e32 v39, -4, v11
	ds_bpermute_b32 v36, v37, v12
	ds_bpermute_b32 v37, v37, v13
	ds_bpermute_b32 v38, v39, v12
	ds_bpermute_b32 v39, v39, v13
	ds_bpermute_b32 v24, v11, v12
	ds_bpermute_b32 v25, v11, v13
	v_add_u32_e32 v11, 32, v11
	v_lshlrev_b32_e32 v41, 16, v224
	v_lshlrev_b32_e32 v40, 16, v228
	v_and_b32_e32 v43, 0xffff0000, v224
	v_and_b32_e32 v42, 0xffff0000, v228
	v_lshlrev_b32_e32 v44, 16, v229
	v_and_b32_e32 v224, 0xffff0000, v229
	v_lshlrev_b32_e32 v229, 16, v226
	v_lshlrev_b32_e32 v228, 16, v230
	v_and_b32_e32 v47, 0xffff0000, v226
	v_and_b32_e32 v46, 0xffff0000, v230
	v_lshlrev_b32_e32 v48, 16, v231
	v_and_b32_e32 v226, 0xffff0000, v231
	s_waitcnt lgkmcnt(14)
	v_pk_mul_f32 v[230:231], v[26:27], v[40:41]
	v_lshlrev_b32_e32 v45, 16, v225
	s_waitcnt lgkmcnt(12)
	v_pk_mul_f32 v[26:27], v[28:29], v[42:43]
	v_add_f32_e32 v15, v230, v231
	v_and_b32_e32 v225, 0xffff0000, v225
	s_waitcnt lgkmcnt(10)
	v_pk_mul_f32 v[28:29], v[30:31], v[44:45]
	v_add_f32_e32 v230, v26, v27
	v_add_f32_e32 v14, v14, v15
	s_waitcnt lgkmcnt(8)
	v_pk_mul_f32 v[224:225], v[32:33], v[224:225]
	v_add_f32_e32 v231, v28, v29
	v_add_f32_e32 v14, v14, v230
	s_waitcnt lgkmcnt(6)
	v_pk_mul_f32 v[228:229], v[34:35], v[228:229]
	v_add_f32_e32 v224, v224, v225
	v_add_f32_e32 v14, v14, v231
	v_lshlrev_b32_e32 v49, 16, v227
	s_waitcnt lgkmcnt(4)
	v_pk_mul_f32 v[30:31], v[36:37], v[46:47]
	v_add_f32_e32 v225, v228, v229
	v_add_f32_e32 v14, v14, v224
	v_and_b32_e32 v227, 0xffff0000, v227
	s_waitcnt lgkmcnt(2)
	v_pk_mul_f32 v[32:33], v[38:39], v[48:49]
	v_add_f32_e32 v228, v30, v31
	v_add_f32_e32 v14, v14, v225
	s_waitcnt lgkmcnt(0)
	v_pk_mul_f32 v[226:227], v[24:25], v[226:227]
	v_add_f32_e32 v229, v32, v33
	v_add_f32_e32 v14, v14, v228
	v_add_f32_e32 v226, v226, v227
	v_add_f32_e32 v14, v14, v229
	v_add_f32_e32 v14, v14, v226
	v_cvt_pk_bf16_f32 v11, v14, s0
	s_lshl_b64 s[0:1], s[4:5], 7
	s_add_i32 s10, s10, s11
	v_lshl_add_u64 v[12:13], v[4:5], 0, s[0:1]
	s_cmpk_gt_i32 s10, 0xff
	global_store_short v[12:13], v11, off
	s_cbranch_scc0 .LBB0_1210
